# layer 1: 40 w_out GEMM tiles run in the tail of the dual projection GEMM behind a release-acquire row counter; P5 tile order rows 0-31 then 32-36
# baseline (speedup 1.0000x reference)
; __device__ __forceinline__ int launder(int v) { asm volatile("" : "+v"(v)); return v; }
; __device__ __forceinline__ void run_phase(const Params& p, int ph, LAS unsigned char* lds, const int tid, const int bid) {
;     ...
;         SchedPlain S; S.init(MPAD, NIN, G, bid); S.A = pws(p) + OFF_XB; S.Bt = pws(p) + OFF_WIN + l * SZ_WIN; S.tstepA = (size_t)256 * D * 2; S.tstepB = (size_t)256 * D * 2;
;         EpiWin E; E.u = (float*)(pws(p) + OFF_U); E.zb = (bf16_t*)(pws(p) + OFF_ZB); E.rsq = (const float*)(pws(p) + OFF_RSQ) + (size_t)l * MPAD; E.cf = (const float*)(pws(p) + OFF_CS);
;         gemm_phase(lds, S, E, D, D, D, tid); }
;     } else if (sub == 1) { if (PH_MASK & 4)
;         for (int it = bid; it < 1024 + 544 + 580; it += G) {
;             if (it < 1024) sample_ret_unit(p, l, it, lds, tid);
;             else if (it < 1568) kv_unit(p, it - 1024, lds, tid);
;             else pool_item(p, l, it - 1568, tid);
;         }
;     } else if (sub == 2) { if (PH_MASK & 8) {
;         for (int it = bid; it + G < 1024; it += 2 * G) scan_item2(p, l, it, it + G, tid); }
;     } else if (sub == 3) { if (PH_MASK & 16) {
;         SchedPool S; S.init(MPAD, D, G, (bid + 128) % G); S.A = pws(p) + OFF_POOLED; S.Bt = pws(p) + OFF_WPOOL + l * SZ_WPOOL;
;         EpiPool E; E.ain = (bf16_t*)(pws(p) + OFF_AIN); E.zb = (const bf16_t*)(pws(p) + OFF_ZB);
;         gemm_phase(lds, S, E, 512, D, 512, tid);
;         for (int it = bid; it < 544; it += G) ret_out_unit(p, l, it, lds, launder(tid)); }
;     } else if (sub == 4) { if (PH_MASK & 32) {
;         SchedDual S; S.init(MPAD, D, G, bid); S.A = pws(p) + OFF_AIN; S.Bt = pws(p) + OFF_WPR + l * SZ_WPR;
;         EpiDual E; E.merged = (bf16_t*)(pws(p) + OFF_MERGED); E.zb = (const bf16_t*)(pws(p) + OFF_ZB);
;         { const int sidx = bid < 40 ? bid : (bid < 80 ? bid - 40 : 0); E.m1 = (float*)(pws(p) + OFF_M1) + ((size_t)l * 40 + sidx) * 65536; E.flag = (unsigned*)(pws(p) + OFF_BAR + 16384) + (l * 40 + sidx) * 64; }
;         gemm_phase(lds, S, E, D, D, D, tid);
;         if (l == 0 && bid >= 80) for (int it = bid - 80; it < 1440; it += G - 80) conv_item(p, 1, it, lds, launder(tid)); }
;     } else { if (PH_MASK & 64) {
;         SchedPlain S; S.init(MPAD, D, G, bid); S.A = pws(p) + OFF_MERGED; S.Bt = pws(p) + OFF_WOUT + l * SZ_WOUT; S.tstepA = (size_t)256 * D * 2; S.tstepB = (size_t)256 * D * 2;
.LBB0_5:
	s_or_b64 exec, exec, s[0:1]
	s_load_dwordx4 s[84:87], s[88:89], 0x68
	s_load_dwordx2 s[6:7], s[88:89], 0x78
	s_load_dwordx16 s[44:59], s[88:89], 0x0
	s_load_dwordx4 s[8:11], s[88:89], 0x40
	s_mul_i32 s0, s43, s42
	v_mov_b32_e32 v234, 0x3ecc95a3
	v_mov_b32_e32 v190, 0x358637bd
	s_waitcnt lgkmcnt(0)
	s_add_u32 s66, s86, 0x4000000
	s_addc_u32 s67, s87, 0
	s_add_u32 s76, s6, 0xb400000
	s_addc_u32 s77, s7, 0
	s_add_u32 s4, s84, 0x1000
	s_addc_u32 s5, s85, 0
	s_add_u32 s2, s84, 0x1400
	s_addc_u32 s3, s85, 0
	s_add_u32 s72, s84, 0x1800
	s_addc_u32 s73, s85, 0
	s_add_u32 s94, s84, 0x1c00
	s_addc_u32 s95, s85, 0
	s_add_u32 s12, s6, 0x41b28000
	s_addc_u32 s13, s7, 0
	s_add_u32 s68, s6, 0xfe00000
	v_writelane_b32 v253, s12, 5
	s_addc_u32 s69, s7, 0
	v_mov_b32_e32 v235, 0x2000
	v_writelane_b32 v253, s13, 6
	s_add_u32 s12, s6, 0x12300000
	s_addc_u32 s13, s7, 0
	v_writelane_b32 v253, s12, 7
	s_add_u32 s1, s6, 0x8000000
	v_mov_b32_e32 v236, 1
	v_writelane_b32 v253, s13, 8
	v_writelane_b32 v253, s1, 9
	s_addc_u32 s1, s7, 0
	s_cmp_lg_u64 s[8:9], 0
	v_writelane_b32 v253, s1, 10
	s_cselect_b64 s[12:13], -1, 0
	v_writelane_b32 v253, s12, 11
	s_cmp_lg_u64 s[54:55], 0
	v_mov_b64_e32 v[246:247], 0x127
	v_writelane_b32 v253, s13, 12
	s_cselect_b64 s[12:13], -1, 0
	s_add_u32 s96, s6, 0x29628000
	v_writelane_b32 v253, s12, 13
	s_addc_u32 s97, s7, 0
	s_add_u32 s1, s6, 0x8400000
	v_writelane_b32 v253, s13, 14
	v_writelane_b32 v253, s1, 15
	s_addc_u32 s1, s7, 0
	s_add_u32 s12, s6, 0x32a28000
	v_writelane_b32 v253, s1, 16
	s_addc_u32 s13, s7, 0
	v_writelane_b32 v253, s12, 17
	v_mov_b64_e32 v[248:249], 0x128
	v_mov_b32_e32 v237, 0x42800000
	v_writelane_b32 v253, s13, 18
	s_add_u32 s12, s6, 0x16e28000
	s_addc_u32 s13, s7, 0
	v_writelane_b32 v253, s12, 19
	s_add_u32 s1, s6, 0x2e028000
	v_mov_b32_e32 v238, 0x7fc00000
	v_writelane_b32 v253, s13, 20
	v_writelane_b32 v253, s1, 21
	s_addc_u32 s1, s7, 0
	v_writelane_b32 v253, s1, 22
	s_add_u32 s1, s6, 0x41d32000
	v_writelane_b32 v253, s1, 23
	s_addc_u32 s1, s7, 0
	v_writelane_b32 v253, s1, 24
	s_ashr_i32 s1, s42, 31
	v_writelane_b32 v253, s1, 25
	s_add_i32 s1, s42, 0xffffffb0
	v_writelane_b32 v253, s1, 26
	s_add_u32 s1, s56, 0x8000000
	v_writelane_b32 v253, s1, 27
	s_addc_u32 s1, s57, 0
	v_writelane_b32 v253, s1, 28
	s_add_u32 s1, s6, 0x4000000
	v_writelane_b32 v253, s1, 29
	s_addc_u32 s1, s7, 0
	v_writelane_b32 v253, s1, 30
	s_load_dword s1, s[88:89], 0x90
	v_mov_b32_e32 v239, 0xff800000
	v_not_b32_e32 v240, 63
	v_mov_b32_e32 v196, 0x3f317218
	v_mov_b32_e32 v241, 0x1e000
	s_waitcnt lgkmcnt(0)
; #define LAS __attribute__((address_space(3)))
; __global__ void __launch_bounds__(512, 2) mega_kernel(Params p, unsigned* bar) {
;     cg::grid_group grid = cg::this_grid();
;     LAS unsigned char* lds = (LAS unsigned char*)smem_dyn;
;     ...
;     volatile LAS unsigned* st = (volatile LAS unsigned*)(lds + LDS_ST_OFF);
;     if (threadIdx.x == 0) { st[0] = 0u; st[1] = 0u; }
;     __syncthreads();
;     (void)xcd_barrier_post(bar, st);
;     int ph = 0, rep = 0;
; #pragma unroll 1
;     while (ph < 14) {
;         int tid = threadIdx.x; asm volatile("" : "+v"(tid));
;         int bid = blockIdx.x; asm volatile("" : "+s"(bid)); bid = __builtin_amdgcn_readfirstlane(bid);
;         run_phase(p, ph, lds, tid, bid);
	s_mul_i32 s0, s0, s1
	v_writelane_b32 v253, s0, 31
	s_add_u32 s0, s54, 0x2000
	s_addc_u32 s1, s55, 0
	v_writelane_b32 v253, s0, 32
	v_mov_b32_e32 v242, 0x37000000
	v_mov_b32_e32 v243, 0x7f800000
	v_writelane_b32 v253, s1, 33
	s_add_u32 s0, s6, 0x27128000
	s_addc_u32 s1, s7, 0
	v_writelane_b32 v253, s0, 34
	s_mov_b32 s78, 0x800000
	s_movk_i32 s74, 0x7000
	v_writelane_b32 v253, s1, 35
	s_add_u32 s0, s6, 0x3d728000
	s_addc_u32 s1, s7, 0
	s_lshl_b32 s60, s42, 1
	s_add_u32 s41, s6, 0x34f28000
	s_addc_u32 s40, s7, 0
	v_writelane_b32 v253, s1, 36
	s_add_u32 s1, s86, 0x48f0000
	v_writelane_b32 v253, s1, 37
	s_addc_u32 s1, s87, 0
	s_add_u32 s12, s6, 0x12428000
	v_writelane_b32 v253, s1, 38
	s_addc_u32 s13, s7, 0
	v_writelane_b32 v253, s12, 39
	s_mov_b32 s75, 0xc2fc0000
	s_mov_b32 s81, 0
	v_writelane_b32 v255, s81, 4
	v_writelane_b32 v255, s81, 5
	v_writelane_b32 v253, s13, 40
	s_add_u32 s12, s86, 0x4800000
	s_addc_u32 s13, s87, 0
	v_writelane_b32 v253, s12, 41
	s_mov_b32 s91, 0
	s_mov_b64 s[92:93], 0x80
	v_writelane_b32 v253, s13, 42
	s_add_u32 s12, s86, 0x58f0000
	s_addc_u32 s13, s87, 0
	v_writelane_b32 v253, s12, 43
	s_add_u32 s1, s86, 0x76f0000
	s_nop 0
	v_writelane_b32 v253, s13, 44
	v_writelane_b32 v253, s1, 45
	s_addc_u32 s1, s87, 0
	v_writelane_b32 v253, s1, 46
	s_add_u32 s1, s6, 0xa400000
	v_writelane_b32 v253, s1, 47
	s_addc_u32 s1, s7, 0
	s_add_u32 s12, s6, 0x12309400
	v_writelane_b32 v253, s1, 48
	s_addc_u32 s13, s7, 0
	v_writelane_b32 v253, s12, 49
	s_sub_i32 s1, s42, 40
	s_nop 0
	v_writelane_b32 v253, s13, 50
	v_writelane_b32 v253, s1, 51
	s_add_u32 s1, s58, 0x400000
	v_writelane_b32 v253, s1, 52
	s_addc_u32 s1, s59, 0
	v_writelane_b32 v253, s1, 53
	s_add_u32 s1, s6, 0x8200000
	v_writelane_b32 v253, s1, 54
	s_addc_u32 s1, s7, 0
	v_writelane_b32 v253, s1, 55
	s_add_u32 s1, s8, 0x2000
	v_writelane_b32 v253, s1, 56
	v_writelane_b32 v253, s8, 57
	s_addc_u32 s1, s9, 0
	s_nop 0
	v_writelane_b32 v253, s9, 58
	v_writelane_b32 v253, s10, 59
	v_writelane_b32 v253, s11, 60
	s_add_u32 s8, s70, 0x200
	v_writelane_b32 v253, s1, 61
	s_addc_u32 s9, s71, 0
	v_writelane_b32 v253, s8, 62
	s_nop 1
	v_writelane_b32 v253, s9, 63
	s_add_u32 s8, s70, 0x1000
	s_addc_u32 s9, s71, 0
	v_writelane_b32 v254, s8, 0
	s_nop 1
	v_writelane_b32 v254, s9, 1
	s_add_u32 s8, s70, 0x1100
	s_addc_u32 s9, s71, 0
	v_writelane_b32 v254, s8, 2
	s_nop 1
	v_writelane_b32 v254, s9, 3
	s_add_u32 s8, s70, 0x1200
	s_addc_u32 s9, s71, 0
	v_writelane_b32 v254, s8, 4
	s_nop 1
	v_writelane_b32 v254, s9, 5
	s_add_u32 s8, s70, 0x1300
	s_addc_u32 s9, s71, 0
	v_writelane_b32 v254, s8, 6
	s_nop 1
	v_writelane_b32 v254, s9, 7
	s_add_u32 s8, s70, 0x3400
	s_addc_u32 s9, s71, 0
	v_writelane_b32 v254, s8, 8
	s_nop 1
	v_writelane_b32 v254, s9, 9
	s_add_u32 s8, s70, 0x3500
	s_addc_u32 s9, s71, 0
	v_writelane_b32 v254, s8, 10
	s_cmp_eq_u32 s43, 7
	s_mov_b32 s43, s0
	v_writelane_b32 v254, s9, 11
	s_cselect_b64 s[0:1], -1, 0
	v_writelane_b32 v254, s0, 12
	s_lshl_b32 s8, s42, 5
	s_nop 0
	v_writelane_b32 v254, s1, 13
	s_abs_i32 s0, s42
	v_cvt_f32_u32_e32 v1, s0
	v_writelane_b32 v254, s0, 14
	s_sub_i32 s0, 0, s0
	v_rcp_iflag_f32_e32 v1, v1
	s_nop 0
	v_mul_f32_e32 v1, 0x4f7ffffe, v1
	v_cvt_u32_f32_e32 v1, v1
	s_nop 0
	v_readfirstlane_b32 s1, v1
	s_mul_i32 s0, s0, s1
	s_mul_hi_u32 s0, s1, s0
	s_add_i32 s0, s1, s0
	v_lshrrev_b32_e32 v1, 20, v0
	v_lshrrev_b32_e32 v0, 10, v0
	v_writelane_b32 v254, s0, 15
	v_or_b32_e32 v0, v0, v1
	s_movk_i32 s0, 0x3ff
	v_and_or_b32 v0, v0, s0, v191
	s_lshl_b32 s0, s42, 4
	s_lshl_b32 s1, s42, 8
	v_writelane_b32 v254, s0, 16
	s_add_i32 s9, s1, 0xffffb000
	v_writelane_b32 v254, s9, 17
	s_lshl_b32 s9, s42, 9
	v_writelane_b32 v254, s9, 18
	s_lshl_b32 s9, s42, 10
	s_lshl_b32 s0, s42, 3
	v_writelane_b32 v254, s9, 19
	s_add_u32 s10, s6, 0x12426000
	v_writelane_b32 v254, s6, 20
	s_addc_u32 s11, s7, 0
	v_mov_b32_e32 v1, 0
	v_writelane_b32 v254, s7, 21
	v_writelane_b32 v254, s10, 22
	s_mov_b32 s6, s42
	s_nop 0
	v_writelane_b32 v254, s11, 23
	v_writelane_b32 v254, s6, 24
	v_writelane_b32 v254, s0, 25
	s_addk_i32 s0, 0xfec0
	v_writelane_b32 v254, s0, 26
	v_writelane_b32 v254, s1, 27
	s_add_i32 s0, s1, 0xffffd800
	v_writelane_b32 v254, s0, 28
	v_writelane_b32 v254, s8, 29
	s_add_i32 s0, s8, 0xfffffb00
	v_writelane_b32 v254, s0, 30
	s_add_i32 s0, 0, 0x10400
	v_writelane_b32 v254, s0, 31
	s_add_i32 s0, 0, 0x23ff0
	v_writelane_b32 v254, s0, 32
	s_add_i32 s0, 0, 0x23ff4
	v_writelane_b32 v254, s0, 33
	v_cmp_eq_u32_e64 s[0:1], 0, v0
	s_nop 1
	v_writelane_b32 v254, s0, 34
	s_nop 1
	v_writelane_b32 v254, s1, 35
	v_writelane_b32 v254, s43, 36
	v_writelane_b32 v254, s60, 37
	v_writelane_b32 v254, s41, 38
	v_writelane_b32 v254, s40, 39
	v_writelane_b32 v254, s88, 40
	s_nop 1
	v_writelane_b32 v254, s89, 41
	v_writelane_b32 v254, s84, 42
	s_nop 1
	v_writelane_b32 v254, s85, 43
	v_writelane_b32 v254, s86, 44
	v_writelane_b32 v254, s87, 45
	s_branch .LBB0_9

; #define G_STAGE(bufoff, gbase, voff) do { _Pragma("unroll") for (int _i = 0; _i < 2; ++_i) \
;         __builtin_amdgcn_global_load_lds((const unsigned*)((const char*)(gbase) + (voff)[_i]), (LAS unsigned*)(lds + (bufoff) + ldsw + _i * 8192), 16, 0, 0); } while (0)
; #define G_WAIT_V(n) asm volatile("s_waitcnt vmcnt(" #n ")" ::: "memory")
; #define G_BAR __builtin_amdgcn_s_barrier()
;     __device__ bool next(int i, Unit& u) const {
;         const long L = (long)i * G + c; if (L >= nwg) return false;
;         int wgid = (int)L; { const int q = nwg / NXCD, r = nwg % NXCD, xcd = wgid % NXCD, off = wgid / NXCD; wgid = (xcd < r ? xcd * (q + 1) : r * (q + 1) + (xcd - r) * q) + off; }
;         const int nig = WGM * nN, gid = wgid / nig, fm = gid * WGM, gsz = (nM - fm) < WGM ? (nM - fm) : WGM;
;         u.pm = fm + ((wgid % nig) % gsz); u.pn = (wgid % nig) / gsz; u.mode = 0; return true;
; template <class Epi, class Sched>
; __device__ __forceinline__ void gemm_phase(LAS unsigned char* lds, const Sched& S, const Epi& E, const int K, const int lda, const int ldb, const int tid) {
;     ...
;     G_STAGE(G_SB(0, 0), cB, voffB); G_STAGE(G_SA(0, 0), cA, voffA); G_STAGE(G_SB(0, 1), cB + hstepB, voffB); G_STAGE(G_SA(0, 1), cA + hstepA, voffA);
;     if (wr == 1) G_BAR;
;     G_WAIT_V(4); G_BAR;
;     G_STAGE(G_SB(1, 0), cB + kstep, voffB); G_STAGE(G_SA(1, 0), cA + kstep, voffA); G_STAGE(G_SB(1, 1), cB + hstepB + kstep, voffB);
;     G_WAIT_V(6); G_BAR;
.Lp6_entry:
	s_cmp_lt_u32 s81, 7
	s_cselect_b64 s[0:1], -1, 0
	s_cmpk_gt_i32 s82, 0x127
	v_readfirstlane_b32 s24, v244
	s_cbranch_scc1 .LBB0_96
	v_lshlrev_b32_e32 v0, 4, v244
	s_waitcnt vmcnt(0)
	v_add_u32_e32 v3, 0x2000, v0
	v_ashrrev_i32_e32 v2, 31, v3
	v_lshrrev_b32_e32 v2, 22, v2
	v_add_u32_e32 v2, v3, v2
	v_ashrrev_i32_e32 v2, 10, v2
	v_mul_i32_i24_e32 v4, 0x400, v2
	v_sub_u32_e32 v3, v3, v4
	v_lshrrev_b32_e32 v4, 4, v3
	v_bitop3_b32 v4, v4, v3, 32 bitop3:0x6c
	v_readlane_b32 s6, v254, 46
	v_ashrrev_i32_e32 v3, 31, v4
	v_readlane_b32 s7, v254, 47
	s_mov_b32 s8, s6
	v_lshrrev_b32_e32 v3, 26, v3
	s_mov_b32 s7, s91
	v_writelane_b32 v254, s8, 46
	v_add_u32_e32 v5, v4, v3
	v_lshlrev_b32_e32 v6, 3, v2
	v_writelane_b32 v254, s9, 47
	s_lshl_b64 s[6:7], s[6:7], 23
	v_readlane_b32 s8, v253, 47
	v_ashrrev_i32_e32 v3, 6, v5
	v_and_b32_e32 v6, -16, v6
	s_add_u32 s25, s8, s6
	v_readlane_b32 s6, v253, 48
	v_add_u32_e32 v6, v3, v6
	s_addc_u32 s26, s6, s7
	v_and_b32_e32 v7, 3, v3
	s_mov_b32 s6, 0xfffe0
	v_lshrrev_b32_e32 v8, 2, v6
	v_lshlrev_b32_e32 v9, 1, v6
	v_and_b32_e32 v5, 0xc0, v5
	v_and_or_b32 v7, v6, s6, v7
	v_and_b32_e32 v8, 4, v8
	v_and_b32_e32 v9, 24, v9
	v_sub_u32_e32 v4, v4, v5
	v_or3_b32 v7, v7, v8, v9
	v_lshlrev_b32_e32 v8, 5, v2
	v_ashrrev_i16_sdwa v4, v236, sext(v4) dst_sel:DWORD dst_unused:UNUSED_PAD src0_sel:DWORD src1_sel:BYTE_0
	v_and_b32_e32 v8, 32, v8
	v_bfe_i32 v4, v4, 0, 16
	v_add_lshl_u32 v5, v8, v4, 1
	v_lshl_add_u32 v178, v7, 12, v5
	v_lshl_add_u32 v180, v6, 12, v5
	v_bfe_i32 v5, v244, 27, 1
	v_lshrrev_b32_e32 v5, 22, v5
	v_add_u32_e32 v5, v0, v5
	v_and_b32_e32 v5, 0xfffffc00, v5
	v_sub_u32_e32 v0, v0, v5
	v_lshrrev_b32_e32 v5, 4, v0
	v_ashrrev_i32_e32 v6, 31, v244
	v_bitop3_b32 v0, v5, v0, 32 bitop3:0x6c
	v_lshrrev_b32_e32 v6, 26, v6
	v_ashrrev_i32_e32 v5, 31, v0
	v_add_u32_e32 v6, v244, v6
	v_lshrrev_b32_e32 v5, 26, v5
	v_ashrrev_i32_e32 v6, 6, v6
	v_add_u32_e32 v7, v0, v5
	v_lshlrev_b32_e32 v8, 3, v6
	v_ashrrev_i32_e32 v5, 6, v7
	v_and_b32_e32 v8, -16, v8
	v_add_u32_e32 v8, v5, v8
	v_and_b32_e32 v9, 3, v5
	s_ashr_i32 s28, s82, 31
	v_and_or_b32 v9, v8, s6, v9
	s_lshr_b32 s6, s28, 29
	s_add_i32 s6, s82, s6
	s_ashr_i32 s7, s24, 6
	s_ashr_i32 s8, s6, 3
	s_and_b32 s6, s6, -8
	s_ashr_i32 s10, s24, 8
	s_lshl_b32 s27, s7, 10
	s_sub_i32 s6, s82, s6
	s_cmp_lt_i32 s6, 0
	s_cselect_b32 s9, 38, 37
	s_mul_i32 s6, s9, s6
	s_add_i32 s6, s6, s8
	s_mov_b32 s9, 0
	s_cmp_lt_u32 s81, 7
	s_cbranch_scc1 .Lp6_mapdone
	s_cmpk_lg_u32 s42, 0x100
	s_cbranch_scc1 .Lp6_mapdone
	s_mov_b32 s9, 1
	v_readlane_b32 s8, v255, 5
	s_and_b32 s6, s82, 7
	s_lshl_b32 s6, s6, 5
	s_lshr_b32 s11, s82, 3
	s_add_i32 s6, s6, s11
	s_cmp_eq_u32 s8, 0
	s_cbranch_scc1 .Lp6_noforce
	s_add_i32 s6, s8, 0xd7
	s_mov_b32 s8, 0
	s_nop 0
	v_writelane_b32 v255, s8, 5
	s_branch .Lp6_mapdone
.Lp6_noforce:
	s_cmpk_lt_u32 s6, 0xd8
	s_cbranch_scc1 .Lp6_mapdone
	s_add_i32 s6, s6, 40
.Lp6_mapdone:
	s_nop 0
	v_writelane_b32 v255, s9, 4
	s_ashr_i32 s8, s6, 31
	s_lshr_b32 s8, s8, 26
	s_waitcnt vmcnt(0)
	v_lshrrev_b32_e32 v10, 2, v8
	v_lshlrev_b32_e32 v11, 1, v8
	v_and_b32_e32 v7, 0xc0, v7
	s_add_i32 s8, s6, s8
	v_and_b32_e32 v10, 4, v10
	v_and_b32_e32 v11, 24, v11
	v_sub_u32_e32 v0, v0, v7
	s_ashr_i32 s9, s8, 6
	v_or3_b32 v9, v9, v10, v11
	v_lshlrev_b32_e32 v10, 5, v6
	v_ashrrev_i16_sdwa v0, v236, sext(v0) dst_sel:DWORD dst_unused:UNUSED_PAD src0_sel:DWORD src1_sel:BYTE_0
	s_lshl_b32 s11, s9, 3
	v_and_b32_e32 v10, 32, v10
	v_bfe_i32 v7, v0, 0, 16
	s_sub_i32 s9, 37, s11
	v_add_lshl_u32 v10, v10, v7, 1
	s_min_u32 s12, s9, 8
	s_andn2_b32 s8, s8, 63
	v_lshl_add_u32 v0, v9, 12, v10
	s_sub_i32 s13, s6, s8
	v_cvt_f32_ubyte0_e32 v9, s12
	v_lshl_add_u32 v182, v8, 12, v10
	v_cvt_f32_i32_e32 v8, s13
	v_rcp_iflag_f32_e32 v10, v9
	s_ashr_i32 s6, s13, 30
	s_or_b32 s6, s6, 1
	v_mul_f32_e32 v10, v8, v10
	v_trunc_f32_e32 v10, v10
	v_fma_f32 v8, -v10, v9, v8
	v_cvt_i32_f32_e32 v10, v10
	v_cmp_ge_f32_e64 s[8:9], |v8|, v9
	s_and_b64 s[8:9], s[8:9], exec
	s_cselect_b32 s6, s6, 0
	v_readfirstlane_b32 s8, v10
	s_add_i32 s6, s8, s6
	s_mul_i32 s8, s6, s12
	s_sub_i32 s8, s13, s8
	s_sext_i32_i8 s8, s8
	s_add_i32 s8, s11, s8
	s_ashr_i32 s9, s8, 31
	s_bfe_i64 s[14:15], s[6:7], 0x80000
	s_lshl_b64 s[12:13], s[8:9], 20
	s_lshl_b64 s[14:15], s[14:15], 20
	s_add_u32 s20, s25, s14
	s_addc_u32 s21, s26, s15
	s_add_i32 s29, s27, 0
	s_add_i32 m0, s29, 0x10000
	v_readlane_b32 s14, v253, 17
	global_load_lds_dwordx4 v0, s[20:21]
	s_add_i32 m0, s29, 0x12000
	v_readlane_b32 s15, v253, 18
	s_add_u32 s18, s14, s12
	global_load_lds_dwordx4 v178, s[20:21]
	s_addc_u32 s19, s15, s13
	s_mov_b32 m0, s29
	s_add_i32 s30, s29, 0x2000
	global_load_lds_dwordx4 v182, s[18:19]
	s_mov_b32 m0, s30
	s_add_u32 s12, s20, 0x80000
	global_load_lds_dwordx4 v180, s[18:19]
	s_addc_u32 s13, s21, 0
	s_add_i32 m0, s29, 0x14000
	s_nop 0
	global_load_lds_dwordx4 v0, s[12:13]
	s_add_i32 m0, s29, 0x16000
	s_nop 0
	global_load_lds_dwordx4 v178, s[12:13]
	s_add_u32 s12, s18, 0x80000
	s_addc_u32 s13, s19, 0
	s_add_i32 s31, s29, 0x4000
	s_mov_b32 m0, s31
	s_add_i32 s33, s29, 0x6000
	global_load_lds_dwordx4 v182, s[12:13]
	s_mov_b32 m0, s33
	s_cmp_lg_u32 s10, 1
	global_load_lds_dwordx4 v180, s[12:13]
	s_cbranch_scc1 .LBB0_71
	s_barrier

;     __device__ bool next(int i, Unit& u) const {
;         const long L = (long)i * G + c; if (L >= nwg) return false;
; template <class Epi, class Sched>
; __device__ __forceinline__ void gemm_phase(LAS unsigned char* lds, const Sched& S, const Epi& E, const int K, const int lda, const int ldb, const int tid) {
;     ...
;         const bool has_next = S.next(ui + 1, nxt);
.LBB0_73:
	s_add_i32 s36, s36, 1
	v_readlane_b32 s6, v253, 25
	v_readlane_b32 s11, v254, 24
	s_mul_i32 s6, s36, s6
	s_mul_hi_u32 s7, s36, s11
	s_add_i32 s7, s7, s6
	s_mul_i32 s6, s36, s11
	s_add_u32 s14, s6, s82
	s_addc_u32 s15, s7, s28
	v_readlane_b32 s6, v255, 4
	s_nop 0
	s_lshl_b32 s6, s6, 12
	s_add_u32 s14, s14, s6
	s_addc_u32 s15, s15, 0
	v_cmp_gt_i64_e64 s[6:7], s[14:15], v[246:247]
	s_and_b64 vcc, exec, s[6:7]
	s_cbranch_vccnz .LBB0_75
	s_ashr_i32 s10, s14, 31
	s_lshr_b32 s10, s10, 29
	s_add_i32 s10, s14, s10
	s_ashr_i32 s11, s10, 3
	s_and_b32 s10, s10, -8
	s_sub_i32 s10, s14, s10
	s_cmp_lt_i32 s10, 0
	s_cselect_b32 s12, 38, 37
	s_mul_i32 s10, s12, s10
	s_add_i32 s10, s10, s11
	s_ashr_i32 s11, s10, 31
	s_lshr_b32 s11, s11, 26
	s_add_i32 s11, s10, s11
	s_ashr_i32 s12, s11, 6
	s_lshl_b32 s12, s12, 3
	s_sub_i32 s13, 37, s12
	s_min_i32 s13, s13, 8
	s_abs_i32 s16, s13
	v_cvt_f32_u32_e32 v2, s16
	s_sub_i32 s22, 0, s16
	s_andn2_b32 s11, s11, 63
	s_sub_i32 s11, s10, s11
	v_rcp_iflag_f32_e32 v2, v2
	s_abs_i32 s10, s11
	s_xor_b32 s17, s11, s13
	s_ashr_i32 s17, s17, 31
	v_mul_f32_e32 v2, 0x4f7ffffe, v2
	v_cvt_u32_f32_e32 v2, v2
	s_nop 0
	v_readfirstlane_b32 s23, v2
	s_mul_i32 s22, s22, s23
	s_mul_hi_u32 s22, s23, s22
	s_add_i32 s23, s23, s22
	s_mul_hi_u32 s22, s10, s23
	s_mul_i32 s23, s22, s16
	s_sub_i32 s10, s10, s23
	s_add_i32 s37, s22, 1
	s_sub_i32 s23, s10, s16
	s_cmp_ge_u32 s10, s16
	s_cselect_b32 s22, s37, s22
	s_cselect_b32 s10, s23, s10
	s_add_i32 s23, s22, 1
	s_cmp_ge_u32 s10, s16
	s_cselect_b32 s10, s23, s22
	s_xor_b32 s10, s10, s17
	s_sub_i32 s10, s10, s17
	s_mul_i32 s13, s10, s13
	s_sub_i32 s11, s11, s13
	s_add_i32 s12, s11, s12

;     __device__ bool next(int i, Unit& u) const {
;         const long L = (long)i * G + c; if (L >= nwg) return false;
;         int wgid = (int)L; { const int q = nwg / NXCD, r = nwg % NXCD, xcd = wgid % NXCD, off = wgid / NXCD; wgid = (xcd < r ? xcd * (q + 1) : r * (q + 1) + (xcd - r) * q) + off; }
;         const int nig = WGM * nN, gid = wgid / nig, fm = gid * WGM, gsz = (nM - fm) < WGM ? (nM - fm) : WGM;
;         u.pm = fm + ((wgid % nig) % gsz); u.pn = (wgid % nig) / gsz; u.mode = 0; return true;
;     __device__ bool next(int i, Unit& u) const {
;         if (i < 2) { if (!StaticOrder::next(0, u)) return false; u.mode = i; return true; }
.LBB0_140:
	s_and_b64 vcc, exec, s[0:1]
	s_cbranch_vccz .LBB0_281
	s_cmpk_lt_i32 s82, 0x128
	s_cselect_b64 s[6:7], -1, 0
	s_cmpk_gt_i32 s82, 0x127
	v_readfirstlane_b32 s63, v244
	s_cbranch_scc1 .LBB0_143
	s_ashr_i32 s0, s82, 31
	s_lshr_b32 s0, s0, 29
	s_add_i32 s0, s82, s0
	s_ashr_i32 s1, s0, 3
	s_and_b32 s0, s0, -8
	s_sub_i32 s0, s82, s0
	s_cmp_lt_i32 s0, 0
	s_cselect_b32 s8, 38, 37
	s_cmpk_eq_u32 s42, 0x100
	s_cselect_b32 s8, 32, s8
	s_mul_i32 s0, s8, s0
	s_add_i32 s0, s0, s1
	s_ashr_i32 s1, s0, 31
	s_lshr_b32 s1, s1, 26
	s_add_i32 s1, s0, s1
	s_ashr_i32 s8, s1, 6
	s_lshl_b32 s8, s8, 3
	s_sub_i32 s9, 37, s8
	s_min_u32 s9, s9, 8
	s_andn2_b32 s1, s1, 63
	s_sub_i32 s10, s0, s1
	s_waitcnt vmcnt(0)
	v_cvt_f32_ubyte0_e32 v2, s9
	v_cvt_f32_i32_e32 v0, s10
	v_rcp_iflag_f32_e32 v3, v2
	s_ashr_i32 s0, s10, 30
	s_or_b32 s11, s0, 1
	v_mul_f32_e32 v3, v0, v3
	v_trunc_f32_e32 v3, v3
	v_fma_f32 v0, -v3, v2, v0
	v_cvt_i32_f32_e32 v3, v3
	v_cmp_ge_f32_e64 s[0:1], |v0|, v2
	s_and_b64 s[0:1], s[0:1], exec
	s_cselect_b32 s0, s11, 0
	v_readfirstlane_b32 s1, v3
	s_add_i32 s1, s1, s0
	s_sext_i32_i8 s0, s1
	s_mul_i32 s1, s1, s9
	s_sub_i32 s1, s10, s1
	s_sext_i32_i8 s1, s1
	s_add_i32 s10, s8, s1

;     __device__ bool next(int i, Unit& u) const {
;     ...
;         if (i == 2 && c < 80) { StaticOrder t = *this; t.c = c < 40 ? c : c - 40; if (!t.next(1, u)) return false; u.mode = c < 40 ? 2 : 3; return true; }
; __device__ __forceinline__ void run_phase(const Params& p, int ph, LAS unsigned char* lds, const int tid, const int bid) {
;     ...
;         { const int sidx = bid < 40 ? bid : (bid < 80 ? bid - 40 : 0); E.m1 = (float*)(pws(p) + OFF_M1) + ((size_t)l * 40 + sidx) * 65536; E.flag = (unsigned*)(pws(p) + OFF_BAR + 16384) + (l * 40 + sidx) * 64; }
.LBB0_146:
	s_sub_i32 s1, s82, 40
	s_cmpk_lt_i32 s82, 0x50
	s_cselect_b64 s[12:13], -1, 0
	s_and_b64 s[14:15], s[12:13], exec
	s_cselect_b32 s8, s1, 0
	s_cmp_lt_i32 s82, 40
	s_cselect_b32 s8, s82, s8
	s_mul_i32 s14, s16, 40
	s_cselect_b32 s1, s82, s1
	s_cselect_b32 s79, 2, 3
	s_ashr_i32 s15, s8, 31
	s_mul_hi_u32 s11, s16, 40
	s_add_u32 s14, s14, s8
	s_addc_u32 s15, s11, s15
	s_lshl_b64 s[14:15], s[14:15], 18
	v_readlane_b32 s11, v253, 21
	s_mov_b32 s18, s16
	s_mul_i32 s16, s16, 40
	s_add_u32 s11, s11, s14
	v_readlane_b32 s14, v253, 22
	s_addc_u32 s20, s14, s15
	s_add_i32 s8, s8, s16
	s_lshl_b32 s14, s8, 6
	s_ashr_i32 s15, s14, 31
	s_lshl_b64 s[14:15], s[14:15], 2
	v_readlane_b32 s8, v253, 23
	v_bfe_u32 v16, v244, 4, 2
	s_add_u32 s14, s8, s14
	v_readlane_b32 s8, v253, 24
	v_and_b32_e32 v15, 15, v244
	v_lshlrev_b32_e32 v18, 4, v16
	v_lshlrev_b32_e32 v19, 2, v244
	s_addc_u32 s15, s8, s15
	v_lshl_or_b32 v18, v15, 6, v18
	s_and_b32 s6, s6, 3
	s_lshl_b32 s8, s7, 13
	v_and_b32_e32 v19, 32, v19
	s_add_i32 m0, s36, 0x18000
	v_lshl_add_u64 v[8:9], v[8:9], 0, s[92:93]
	v_bitop3_b32 v20, v18, s8, v19 bitop3:0xde
	s_lshl_b32 s8, s6, 12
	s_waitcnt vmcnt(4)
	s_barrier
	global_load_lds_dwordx4 v[8:9], off
	v_lshl_add_u64 v[6:7], v[6:7], 0, s[92:93]
	s_add_i32 m0, s36, 0x1a000
	s_add_i32 s41, s36, 0x8000
	s_add_i32 s83, s36, 0xa000
	global_load_lds_dwordx4 v[6:7], off
	v_lshl_add_u64 v[4:5], v[4:5], 0, s[92:93]
	s_mov_b32 m0, s41
	s_add_u32 s16, s24, 0x80080
	global_load_lds_dwordx4 v[4:5], off
	v_lshl_add_u64 v[2:3], v[2:3], 0, s[92:93]
	s_mov_b32 m0, s83
	s_addc_u32 s17, s25, 0
	global_load_lds_dwordx4 v[2:3], off
	s_add_i32 m0, s36, 0x1c000
	v_lshl_add_u64 v[2:3], s[16:17], 0, v[178:179]
	global_load_lds_dwordx4 v[2:3], off
	v_lshl_add_u64 v[2:3], s[16:17], 0, v[182:183]
	s_add_i32 m0, s36, 0x1e000
	v_lshl_or_b32 v197, s7, 6, v15
	global_load_lds_dwordx4 v[2:3], off
	s_lshl_b32 s7, s7, 2
	v_writelane_b32 v254, s18, 46
	s_or_b32 s16, s7, s6
	s_ashr_i32 s17, s16, 31
	v_writelane_b32 v254, s19, 47
	v_bitop3_b32 v245, s8, v18, v19 bitop3:0xf6
	s_lshl_b64 s[16:17], s[16:17], 15
	s_ashr_i32 s8, s1, 31
	v_readlane_b32 s18, v254, 24
	s_add_u32 s18, s1, s18
	v_readlane_b32 s1, v253, 25
	s_addc_u32 s19, s8, s1
	s_ashr_i32 s1, s18, 31
	s_lshr_b32 s1, s1, 29
	s_add_i32 s1, s18, s1
	s_ashr_i32 s8, s1, 3
	s_and_b32 s1, s1, -8
	v_cmp_lt_i64_e64 s[86:87], s[18:19], v[248:249]
	s_sub_i32 s1, s18, s1
	s_ashr_i32 s18, s82, 31
	s_lshr_b32 s18, s18, 29
	s_add_i32 s18, s82, s18
	s_ashr_i32 s19, s18, 3
	s_and_b32 s18, s18, -8
	s_sub_i32 s18, s82, s18
	s_add_u32 s16, s11, s16
	s_addc_u32 s17, s20, s17
	s_cmp_lt_i32 s1, 0
	s_cselect_b32 s11, 38, 37
	s_mul_i32 s1, s11, s1
	s_add_i32 s1, s1, s8
	s_cmpk_lg_u32 s42, 0x100
	s_cbranch_scc1 .Lp5_r2map_done
	s_sub_i32 s11, s82, 40
	s_cmp_lt_i32 s82, 40
	s_cselect_b32 s11, s82, s11
	s_add_i32 s1, s11, 0x100
;     __device__ bool next(int i, Unit& u) const {
;         const long L = (long)i * G + c; if (L >= nwg) return false;
;         int wgid = (int)L; { const int q = nwg / NXCD, r = nwg % NXCD, xcd = wgid % NXCD, off = wgid / NXCD; wgid = (xcd < r ? xcd * (q + 1) : r * (q + 1) + (xcd - r) * q) + off; }
;         const int nig = WGM * nN, gid = wgid / nig, fm = gid * WGM, gsz = (nM - fm) < WGM ? (nM - fm) : WGM;
;         u.pm = fm + ((wgid % nig) % gsz); u.pn = (wgid % nig) / gsz; u.mode = 0; return true;
; template <class Epi, class Sched>
; __device__ __forceinline__ void gemm_phase(LAS unsigned char* lds, const Sched& S, const Epi& E, const int K, const int lda, const int ldb, const int tid) {
;     ...
;     f32x4 acc[2][2][4][2];
; #pragma unroll
;     for (int a = 0; a < 2; ++a)
; #pragma unroll
;         for (int b = 0; b < 2; ++b)
; #pragma unroll
;             for (int m = 0; m < 4; ++m)
; #pragma unroll
;                 for (int n = 0; n < 2; ++n) acc[a][b][m][n] = (f32x4){0.f, 0.f, 0.f, 0.f};
.Lp5_r2map_done:
	s_ashr_i32 s8, s1, 31
	s_lshr_b32 s8, s8, 26
	s_add_i32 s8, s1, s8
	s_ashr_i32 s11, s8, 6
	s_lshl_b32 s11, s11, 3
	s_sub_i32 s20, 37, s11
	s_andn2_b32 s8, s8, 63
	s_min_i32 s20, s20, 8
	s_sub_i32 s1, s1, s8
	s_cmp_lt_i32 s18, 0
	v_lshlrev_b32_e32 v17, 3, v16
	v_or_b32_e32 v2, v16, v15
	s_cselect_b32 s8, 38, 37
	s_abs_i32 s21, s20
	v_lshl_or_b32 v246, s6, 5, v17
	v_cmp_eq_u32_e64 s[6:7], 0, v2
	v_cvt_f32_u32_e32 v2, s21
	s_cmpk_eq_u32 s42, 0x100
	s_cselect_b32 s8, 32, s8
	s_mul_i32 s8, s8, s18
	s_add_i32 s8, s8, s19
	s_ashr_i32 s18, s8, 31
	v_rcp_iflag_f32_e32 v2, v2
	s_lshr_b32 s18, s18, 26
	s_sub_i32 s28, 0, s21
	s_add_i32 s18, s8, s18
	v_mul_f32_e32 v2, 0x4f7ffffe, v2
	v_cvt_u32_f32_e32 v2, v2
	s_ashr_i32 s19, s18, 6
	s_lshl_b32 s19, s19, 3
	s_abs_i32 s23, s1
	v_readfirstlane_b32 s29, v2
	s_mul_i32 s28, s28, s29
	s_mul_hi_u32 s28, s29, s28
	s_add_i32 s29, s29, s28
	s_sub_i32 s22, 37, s19
	s_mul_hi_u32 s28, s23, s29
	s_min_u32 s22, s22, 8
	s_andn2_b32 s18, s18, 63
	s_mul_i32 s29, s28, s21
	s_sub_i32 s8, s8, s18
	s_xor_b32 s18, s1, s20
	s_sub_i32 s23, s23, s29
	v_cvt_f32_ubyte0_e32 v2, s22
	s_ashr_i32 s18, s18, 31
	s_add_i32 s29, s28, 1
	s_sub_i32 s30, s23, s21
	v_rcp_iflag_f32_e32 v2, v2
	s_cmp_ge_u32 s23, s21
	s_cselect_b32 s28, s29, s28
	s_cselect_b32 s23, s30, s23
	s_add_i32 s29, s28, 1
	s_cmp_ge_u32 s23, s21
	v_mul_f32_e32 v2, 0x4f7ffffe, v2
	s_cselect_b32 s21, s29, s28
	v_cvt_u32_f32_e32 v2, v2
	s_xor_b32 s21, s21, s18
	s_sub_i32 s80, s21, s18
	s_mul_i32 s18, s80, s20
	s_sub_i32 s1, s1, s18
	s_sub_i32 s18, 0, s22
	v_readfirstlane_b32 s20, v2
	s_mul_i32 s18, s18, s20
	s_mul_hi_u32 s18, s20, s18
	s_add_i32 s88, s1, s11
	s_abs_i32 s11, s8
	s_add_i32 s20, s20, s18
	s_mul_hi_u32 s18, s11, s20
	s_mul_i32 s20, s18, s22
	s_sub_i32 s11, s11, s20
	s_ashr_i32 s1, s8, 31
	s_add_i32 s20, s18, 1
	s_sub_i32 s21, s11, s22
	s_cmp_ge_u32 s11, s22
	v_lshlrev_b32_e32 v2, 15, v0
	s_cselect_b32 s18, s20, s18
	v_and_b32_e32 v2, 0xffff0000, v2
	s_cselect_b32 s11, s21, s11
	s_add_i32 s20, s18, 1
	v_lshl_add_u32 v2, v10, 12, v2
	v_and_b32_e32 v0, 1, v0
	s_cmp_ge_u32 s11, s22
	v_lshl_or_b32 v0, v0, 6, v2
	s_cselect_b32 s11, s20, s18
	v_lshl_add_u32 v184, v11, 1, v0
	v_lshlrev_b32_e32 v0, 15, v12
	s_xor_b32 s11, s11, s1
	v_and_b32_e32 v0, 0xffff0000, v0
	s_sub_i32 s30, s11, s1
	v_lshl_add_u32 v0, v13, 12, v0
	v_and_b32_e32 v2, 1, v12
	s_waitcnt vmcnt(6)
	s_mul_i32 s1, s30, s22
	v_lshl_or_b32 v0, v2, 6, v0
	v_mov_b32_e32 v2, v1
	v_mov_b32_e32 v3, v1
	s_sub_i32 s8, s8, s1
	v_lshl_add_u32 v186, v14, 1, v0
	v_mov_b32_e32 v0, v1
	v_add_u32_e32 v248, 0, v20
	v_mov_b64_e32 v[54:55], v[2:3]
	v_mov_b64_e32 v[50:51], v[2:3]
	v_mov_b64_e32 v[94:95], v[2:3]
	v_mov_b64_e32 v[46:47], v[2:3]
	v_mov_b64_e32 v[90:91], v[2:3]
	v_mov_b64_e32 v[42:43], v[2:3]
	v_mov_b64_e32 v[82:83], v[2:3]
	v_mov_b64_e32 v[38:39], v[2:3]
	v_mov_b64_e32 v[98:99], v[2:3]
	v_mov_b64_e32 v[34:35], v[2:3]
	v_mov_b64_e32 v[114:115], v[2:3]
	v_mov_b64_e32 v[118:119], v[2:3]
	v_mov_b64_e32 v[86:87], v[2:3]
	v_mov_b64_e32 v[30:31], v[2:3]
	v_mov_b64_e32 v[110:111], v[2:3]
	v_mov_b64_e32 v[122:123], v[2:3]
	v_mov_b64_e32 v[78:79], v[2:3]
	v_mov_b64_e32 v[26:27], v[2:3]
	v_mov_b64_e32 v[70:71], v[2:3]
	v_mov_b64_e32 v[22:23], v[2:3]
	v_mov_b64_e32 v[66:67], v[2:3]
	v_mov_b64_e32 v[18:19], v[2:3]
	v_mov_b64_e32 v[58:59], v[2:3]
	v_mov_b64_e32 v[14:15], v[2:3]
	v_mov_b64_e32 v[74:75], v[2:3]
	v_mov_b64_e32 v[10:11], v[2:3]
	v_mov_b64_e32 v[106:107], v[2:3]
	v_mov_b64_e32 v[134:135], v[2:3]
	v_mov_b64_e32 v[62:63], v[2:3]
	v_mov_b64_e32 v[6:7], v[2:3]
	v_mov_b64_e32 v[102:103], v[2:3]
	v_mov_b64_e32 v[146:147], v[2:3]
	s_mov_b32 s9, 0
	v_and_b32_e32 v247, 63, v244
	s_add_i32 s8, s8, s19
	v_mov_b32_e32 v185, v1
	v_mov_b32_e32 v187, v1
	v_mov_b64_e32 v[52:53], v[0:1]
	v_mov_b64_e32 v[48:49], v[0:1]
	v_mov_b64_e32 v[92:93], v[0:1]
	v_mov_b64_e32 v[44:45], v[0:1]
	v_mov_b64_e32 v[88:89], v[0:1]
	v_mov_b64_e32 v[40:41], v[0:1]
	v_mov_b64_e32 v[80:81], v[0:1]
	v_mov_b64_e32 v[36:37], v[0:1]
	v_mov_b64_e32 v[96:97], v[0:1]
	v_mov_b64_e32 v[32:33], v[0:1]
	v_mov_b64_e32 v[112:113], v[0:1]
	v_mov_b64_e32 v[116:117], v[0:1]
	v_mov_b64_e32 v[84:85], v[0:1]
	v_mov_b64_e32 v[28:29], v[0:1]
	v_mov_b64_e32 v[108:109], v[0:1]
	v_mov_b64_e32 v[120:121], v[0:1]
	v_mov_b64_e32 v[76:77], v[0:1]
	v_mov_b64_e32 v[24:25], v[0:1]
	v_mov_b64_e32 v[68:69], v[0:1]
	v_mov_b64_e32 v[20:21], v[0:1]
	v_mov_b64_e32 v[64:65], v[0:1]
	v_mov_b64_e32 v[16:17], v[0:1]
	v_mov_b64_e32 v[56:57], v[0:1]
	v_mov_b64_e32 v[12:13], v[0:1]
	v_mov_b64_e32 v[72:73], v[0:1]
	v_mov_b64_e32 v[8:9], v[0:1]
	v_mov_b64_e32 v[104:105], v[0:1]
	v_mov_b64_e32 v[132:133], v[0:1]
	v_mov_b64_e32 v[60:61], v[0:1]
	v_mov_b64_e32 v[4:5], v[0:1]
	v_mov_b64_e32 v[100:101], v[0:1]
	v_mov_b64_e32 v[144:145], v[0:1]
	s_mov_b32 s85, 0
	s_barrier
	s_branch .LBB0_149

;     __device__ __forceinline__ bool operator()(f32x4 (&acc)[2][2][4][2], const Unit& un, int wr, int wc, int fr, int fq) const {
;     ...
;             asm volatile("s_waitcnt vmcnt(0)" ::: "memory");
;             __builtin_amdgcn_fence(__ATOMIC_RELEASE, "agent");
;             asm volatile("s_waitcnt vmcnt(0)" ::: "memory");
;             if (fr == 0 && fq == 0) __hip_atomic_fetch_add(flag, 1u, __ATOMIC_RELAXED, __HIP_MEMORY_SCOPE_AGENT);
.LBB0_148:
	s_cmp_eq_u32 s81, 11
	s_cbranch_scc0 .Lp5_nosig
	s_cmp_eq_u32 s85, 2
	s_cbranch_scc0 .Lp5_nosig
	s_cmpk_lg_u32 s42, 0x100
	s_cbranch_scc1 .Lp5_nosig
	s_and_b32 s22, s82, 7
	s_cmp_lt_u32 s22, 6
	s_cbranch_scc1 .Lp5_nosig
	v_readlane_b32 s22, v253, 23
	v_readlane_b32 s23, v253, 24
	s_waitcnt vmcnt(0)
	buffer_wbl2 sc1
	s_waitcnt vmcnt(0)
	s_add_u32 s22, s22, 0x6000
	s_addc_u32 s23, s23, 0
	s_mov_b64 vcc, exec
	s_mov_b64 exec, 1
	s_nop 4
	global_atomic_add v1, v236, s[22:23]
	s_mov_b64 exec, vcc

; __device__ __forceinline__ int launder(int v) { asm volatile("" : "+v"(v)); return v; }
;     __device__ __forceinline__ bool operator()(f32x4 (&acc)[2][2][4][2], const Unit& un, int wr, int wc, int fr, int fq) const {
;     ...
;             while (__hip_atomic_load(flag, __ATOMIC_RELAXED, __HIP_MEMORY_SCOPE_AGENT) < 8u) { __builtin_amdgcn_s_sleep(2); if (++sp > (1u << 22)) break; }
;             __builtin_amdgcn_fence(__ATOMIC_ACQUIRE, "agent");
;             asm volatile("s_waitcnt vmcnt(0)" ::: "memory");
; __device__ __forceinline__ void run_phase(const Params& p, int ph, LAS unsigned char* lds, const int tid, const int bid) {
;     ...
;         if (l == 0 && bid >= 80) for (int it = bid - 80; it < 1440; it += G - 80) conv_item(p, 1, it, lds, launder(tid)); }
.LBB0_262:
	s_cmp_eq_u32 s81, 11
	s_cbranch_scc0 .Lp5_noshadow
	s_cmpk_lg_u32 s42, 0x100
	s_cbranch_scc1 .Lp5_noshadow
	s_cmpk_lt_u32 s82, 0x50
	s_cbranch_scc1 .Lp5_noshadow
	s_cmpk_gt_u32 s82, 0x77
	s_cbranch_scc1 .Lp5_noshadow
	v_readlane_b32 s6, v253, 23
	v_readlane_b32 s7, v253, 24
	s_movk_i32 s8, 0x4000
	s_add_u32 s6, s6, 0x6000
	s_addc_u32 s7, s7, 0
	s_nop 4
.Lp5_spin:
	global_load_dword v2, v1, s[6:7] sc1
	s_waitcnt vmcnt(0)
	v_readfirstlane_b32 s9, v2
	s_nop 0
	s_cmpk_ge_u32 s9, 0x200
	s_cbranch_scc1 .Lp5_spun
	s_sleep 2
	s_sub_i32 s8, s8, 1
	s_cmp_lg_u32 s8, 0
	s_cbranch_scc1 .Lp5_spin
.Lp5_spun:
	buffer_inv sc1
	s_waitcnt vmcnt(0)
	s_add_i32 s8, s82, 0xffffffb1
	s_nop 0
	v_writelane_b32 v255, s8, 5
	s_branch .Lp6_entry
